# LayerNorm after FFN-down, sample rows: the 11 split-K partial rows are summed with 16 loads in flight and counted waits (was ~17 dependent round trips)
# speedup vs baseline: 1.0050x; 1.0050x over previous
.LBB0_1443:
	s_andn2_b64 vcc, exec, s[18:19]
	s_cbranch_vccnz .LBB0_1448
	s_lshl_b64 s[18:19], s[92:93], 12
	v_lshl_add_u64 v[126:127], v[124:125], 0, s[18:19]
	s_mov_b32 s19, 0
	global_load_dwordx4 v[168:171], v[126:127], off
	global_load_dwordx4 v[172:175], v[126:127], off offset:1024
	global_load_dwordx4 v[176:179], v[126:127], off offset:2048
	global_load_dwordx4 v[180:183], v[126:127], off offset:3072
	s_mov_b32 s18, 0x200000
	v_lshl_add_u64 v[198:199], v[126:127], 0, s[18:19]
	global_load_dwordx4 v[184:187], v[198:199], off
	global_load_dwordx4 v[188:191], v[198:199], off offset:1024
	global_load_dwordx4 v[192:195], v[198:199], off offset:2048
	global_load_dwordx4 v[212:215], v[198:199], off offset:3072
	s_mov_b32 s18, 0x400000
	v_lshl_add_u64 v[206:207], v[126:127], 0, s[18:19]
	global_load_dwordx4 v[216:219], v[206:207], off
	global_load_dwordx4 v[222:225], v[206:207], off offset:1024
	global_load_dwordx4 v[226:229], v[206:207], off offset:2048
	global_load_dwordx4 v[230:233], v[206:207], off offset:3072
	s_mov_b32 s18, 0x600000
	v_lshl_add_u64 v[198:199], v[126:127], 0, s[18:19]
	global_load_dwordx4 v[234:237], v[198:199], off
	global_load_dwordx4 v[238:241], v[198:199], off offset:1024
	global_load_dwordx4 v[242:245], v[198:199], off offset:2048
	global_load_dwordx4 v[246:249], v[198:199], off offset:3072
	s_waitcnt vmcnt(15)
	v_pk_add_f32 v[100:101], v[100:101], v[168:169]
	v_pk_add_f32 v[102:103], v[102:103], v[170:171]
	s_waitcnt vmcnt(14)
	v_pk_add_f32 v[104:105], v[104:105], v[172:173]
	v_pk_add_f32 v[106:107], v[106:107], v[174:175]
	s_waitcnt vmcnt(13)
	v_pk_add_f32 v[108:109], v[108:109], v[176:177]
	v_pk_add_f32 v[110:111], v[110:111], v[178:179]
	s_waitcnt vmcnt(12)
	v_pk_add_f32 v[96:97], v[96:97], v[180:181]
	v_pk_add_f32 v[98:99], v[98:99], v[182:183]
	s_waitcnt vmcnt(11)
	v_pk_add_f32 v[100:101], v[100:101], v[184:185]
	v_pk_add_f32 v[102:103], v[102:103], v[186:187]
	s_waitcnt vmcnt(10)
	v_pk_add_f32 v[104:105], v[104:105], v[188:189]
	v_pk_add_f32 v[106:107], v[106:107], v[190:191]
	s_waitcnt vmcnt(9)
	v_pk_add_f32 v[108:109], v[108:109], v[192:193]
	v_pk_add_f32 v[110:111], v[110:111], v[194:195]
	s_waitcnt vmcnt(8)
	v_pk_add_f32 v[96:97], v[96:97], v[212:213]
	v_pk_add_f32 v[98:99], v[98:99], v[214:215]
	s_waitcnt vmcnt(7)
	v_pk_add_f32 v[100:101], v[100:101], v[216:217]
	v_pk_add_f32 v[102:103], v[102:103], v[218:219]
	s_waitcnt vmcnt(6)
	v_pk_add_f32 v[104:105], v[104:105], v[222:223]
	v_pk_add_f32 v[106:107], v[106:107], v[224:225]
	s_waitcnt vmcnt(5)
	v_pk_add_f32 v[108:109], v[108:109], v[226:227]
	v_pk_add_f32 v[110:111], v[110:111], v[228:229]
	s_waitcnt vmcnt(4)
	v_pk_add_f32 v[96:97], v[96:97], v[230:231]
	v_pk_add_f32 v[98:99], v[98:99], v[232:233]
	s_waitcnt vmcnt(3)
	v_pk_add_f32 v[100:101], v[100:101], v[234:235]
	v_pk_add_f32 v[102:103], v[102:103], v[236:237]
	s_waitcnt vmcnt(2)
	v_pk_add_f32 v[104:105], v[104:105], v[238:239]
	v_pk_add_f32 v[106:107], v[106:107], v[240:241]
	s_waitcnt vmcnt(1)
	v_pk_add_f32 v[108:109], v[108:109], v[242:243]
	v_pk_add_f32 v[110:111], v[110:111], v[244:245]
	s_waitcnt vmcnt(0)
	v_pk_add_f32 v[96:97], v[96:97], v[246:247]
	v_pk_add_f32 v[98:99], v[98:99], v[248:249]
	s_mov_b32 s18, 0x800000
	v_lshl_add_u64 v[206:207], v[126:127], 0, s[18:19]
	global_load_dwordx4 v[168:171], v[206:207], off
	global_load_dwordx4 v[172:175], v[206:207], off offset:1024
	global_load_dwordx4 v[176:179], v[206:207], off offset:2048
	global_load_dwordx4 v[180:183], v[206:207], off offset:3072
	s_mov_b32 s18, 0xa00000
	v_lshl_add_u64 v[198:199], v[126:127], 0, s[18:19]
	global_load_dwordx4 v[184:187], v[198:199], off
	global_load_dwordx4 v[188:191], v[198:199], off offset:1024
	global_load_dwordx4 v[192:195], v[198:199], off offset:2048
	global_load_dwordx4 v[212:215], v[198:199], off offset:3072
	s_mov_b32 s18, 0xc00000
	v_lshl_add_u64 v[206:207], v[126:127], 0, s[18:19]
	global_load_dwordx4 v[216:219], v[206:207], off
	global_load_dwordx4 v[222:225], v[206:207], off offset:1024
	global_load_dwordx4 v[226:229], v[206:207], off offset:2048
	global_load_dwordx4 v[230:233], v[206:207], off offset:3072
	s_mov_b32 s18, 0xe00000
	v_lshl_add_u64 v[198:199], v[126:127], 0, s[18:19]
	global_load_dwordx4 v[234:237], v[198:199], off
	global_load_dwordx4 v[238:241], v[198:199], off offset:1024
	global_load_dwordx4 v[242:245], v[198:199], off offset:2048
	global_load_dwordx4 v[246:249], v[198:199], off offset:3072
	s_waitcnt vmcnt(15)
	v_pk_add_f32 v[100:101], v[100:101], v[168:169]
	v_pk_add_f32 v[102:103], v[102:103], v[170:171]
	s_waitcnt vmcnt(14)
	v_pk_add_f32 v[104:105], v[104:105], v[172:173]
	v_pk_add_f32 v[106:107], v[106:107], v[174:175]
	s_waitcnt vmcnt(13)
	v_pk_add_f32 v[108:109], v[108:109], v[176:177]
	v_pk_add_f32 v[110:111], v[110:111], v[178:179]
	s_waitcnt vmcnt(12)
	v_pk_add_f32 v[96:97], v[96:97], v[180:181]
	v_pk_add_f32 v[98:99], v[98:99], v[182:183]
	s_waitcnt vmcnt(11)
	v_pk_add_f32 v[100:101], v[100:101], v[184:185]
	v_pk_add_f32 v[102:103], v[102:103], v[186:187]
	s_waitcnt vmcnt(10)
	v_pk_add_f32 v[104:105], v[104:105], v[188:189]
	v_pk_add_f32 v[106:107], v[106:107], v[190:191]
	s_waitcnt vmcnt(9)
	v_pk_add_f32 v[108:109], v[108:109], v[192:193]
	v_pk_add_f32 v[110:111], v[110:111], v[194:195]
	s_waitcnt vmcnt(8)
	v_pk_add_f32 v[96:97], v[96:97], v[212:213]
	v_pk_add_f32 v[98:99], v[98:99], v[214:215]
	s_waitcnt vmcnt(7)
	v_pk_add_f32 v[100:101], v[100:101], v[216:217]
	v_pk_add_f32 v[102:103], v[102:103], v[218:219]
	s_waitcnt vmcnt(6)
	v_pk_add_f32 v[104:105], v[104:105], v[222:223]
	v_pk_add_f32 v[106:107], v[106:107], v[224:225]
	s_waitcnt vmcnt(5)
	v_pk_add_f32 v[108:109], v[108:109], v[226:227]
	v_pk_add_f32 v[110:111], v[110:111], v[228:229]
	s_waitcnt vmcnt(4)
	v_pk_add_f32 v[96:97], v[96:97], v[230:231]
	v_pk_add_f32 v[98:99], v[98:99], v[232:233]
	s_waitcnt vmcnt(3)
	v_pk_add_f32 v[100:101], v[100:101], v[234:235]
	v_pk_add_f32 v[102:103], v[102:103], v[236:237]
	s_waitcnt vmcnt(2)
	v_pk_add_f32 v[104:105], v[104:105], v[238:239]
	v_pk_add_f32 v[106:107], v[106:107], v[240:241]
	s_waitcnt vmcnt(1)
	v_pk_add_f32 v[108:109], v[108:109], v[242:243]
	v_pk_add_f32 v[110:111], v[110:111], v[244:245]
	s_waitcnt vmcnt(0)
	v_pk_add_f32 v[96:97], v[96:97], v[246:247]
	v_pk_add_f32 v[98:99], v[98:99], v[248:249]
	s_mov_b32 s18, 0x1000000
	v_lshl_add_u64 v[206:207], v[126:127], 0, s[18:19]
	global_load_dwordx4 v[168:171], v[206:207], off
	global_load_dwordx4 v[172:175], v[206:207], off offset:1024
	global_load_dwordx4 v[176:179], v[206:207], off offset:2048
	global_load_dwordx4 v[180:183], v[206:207], off offset:3072
	s_mov_b32 s18, 0x1200000
	v_lshl_add_u64 v[198:199], v[126:127], 0, s[18:19]
	global_load_dwordx4 v[184:187], v[198:199], off
	global_load_dwordx4 v[188:191], v[198:199], off offset:1024
	global_load_dwordx4 v[192:195], v[198:199], off offset:2048
	global_load_dwordx4 v[212:215], v[198:199], off offset:3072
	s_mov_b32 s18, 0x1400000
	v_lshl_add_u64 v[206:207], v[126:127], 0, s[18:19]
	global_load_dwordx4 v[216:219], v[206:207], off
	global_load_dwordx4 v[222:225], v[206:207], off offset:1024
	global_load_dwordx4 v[226:229], v[206:207], off offset:2048
	global_load_dwordx4 v[230:233], v[206:207], off offset:3072
	s_waitcnt vmcnt(11)
	v_pk_add_f32 v[100:101], v[100:101], v[168:169]
	v_pk_add_f32 v[102:103], v[102:103], v[170:171]
	s_waitcnt vmcnt(10)
	v_pk_add_f32 v[104:105], v[104:105], v[172:173]
	v_pk_add_f32 v[106:107], v[106:107], v[174:175]
	s_waitcnt vmcnt(9)
	v_pk_add_f32 v[108:109], v[108:109], v[176:177]
	v_pk_add_f32 v[110:111], v[110:111], v[178:179]
	s_waitcnt vmcnt(8)
	v_pk_add_f32 v[96:97], v[96:97], v[180:181]
	v_pk_add_f32 v[98:99], v[98:99], v[182:183]
	s_waitcnt vmcnt(7)
	v_pk_add_f32 v[100:101], v[100:101], v[184:185]
	v_pk_add_f32 v[102:103], v[102:103], v[186:187]
	s_waitcnt vmcnt(6)
	v_pk_add_f32 v[104:105], v[104:105], v[188:189]
	v_pk_add_f32 v[106:107], v[106:107], v[190:191]
	s_waitcnt vmcnt(5)
	v_pk_add_f32 v[108:109], v[108:109], v[192:193]
	v_pk_add_f32 v[110:111], v[110:111], v[194:195]
	s_waitcnt vmcnt(4)
	v_pk_add_f32 v[96:97], v[96:97], v[212:213]
	v_pk_add_f32 v[98:99], v[98:99], v[214:215]
	s_waitcnt vmcnt(3)
	v_pk_add_f32 v[100:101], v[100:101], v[216:217]
	v_pk_add_f32 v[102:103], v[102:103], v[218:219]
	s_waitcnt vmcnt(2)
	v_pk_add_f32 v[104:105], v[104:105], v[222:223]
	v_pk_add_f32 v[106:107], v[106:107], v[224:225]
	s_waitcnt vmcnt(1)
	v_pk_add_f32 v[108:109], v[108:109], v[226:227]
	v_pk_add_f32 v[110:111], v[110:111], v[228:229]
	s_waitcnt vmcnt(0)
	v_pk_add_f32 v[96:97], v[96:97], v[230:231]
	v_pk_add_f32 v[98:99], v[98:99], v[232:233]
	s_nop 1

.LBB0_1474:
	s_andn2_b64 vcc, exec, s[8:9]
	s_cbranch_vccnz .LBB0_1479
	s_lshl_b64 s[8:9], s[92:93], 12
	v_lshl_add_u64 v[126:127], v[124:125], 0, s[8:9]
	s_mov_b32 s9, 0
	global_load_dwordx4 v[168:171], v[126:127], off
	global_load_dwordx4 v[172:175], v[126:127], off offset:1024
	global_load_dwordx4 v[176:179], v[126:127], off offset:2048
	global_load_dwordx4 v[180:183], v[126:127], off offset:3072
	s_mov_b32 s8, 0x200000
	v_lshl_add_u64 v[198:199], v[126:127], 0, s[8:9]
	global_load_dwordx4 v[184:187], v[198:199], off
	global_load_dwordx4 v[188:191], v[198:199], off offset:1024
	global_load_dwordx4 v[192:195], v[198:199], off offset:2048
	global_load_dwordx4 v[212:215], v[198:199], off offset:3072
	s_mov_b32 s8, 0x400000
	v_lshl_add_u64 v[206:207], v[126:127], 0, s[8:9]
	global_load_dwordx4 v[216:219], v[206:207], off
	global_load_dwordx4 v[222:225], v[206:207], off offset:1024
	global_load_dwordx4 v[226:229], v[206:207], off offset:2048
	global_load_dwordx4 v[230:233], v[206:207], off offset:3072
	s_mov_b32 s8, 0x600000
	v_lshl_add_u64 v[198:199], v[126:127], 0, s[8:9]
	global_load_dwordx4 v[234:237], v[198:199], off
	global_load_dwordx4 v[238:241], v[198:199], off offset:1024
	global_load_dwordx4 v[242:245], v[198:199], off offset:2048
	global_load_dwordx4 v[246:249], v[198:199], off offset:3072
	s_waitcnt vmcnt(15)
	v_pk_add_f32 v[100:101], v[100:101], v[168:169]
	v_pk_add_f32 v[102:103], v[102:103], v[170:171]
	s_waitcnt vmcnt(14)
	v_pk_add_f32 v[104:105], v[104:105], v[172:173]
	v_pk_add_f32 v[106:107], v[106:107], v[174:175]
	s_waitcnt vmcnt(13)
	v_pk_add_f32 v[108:109], v[108:109], v[176:177]
	v_pk_add_f32 v[110:111], v[110:111], v[178:179]
	s_waitcnt vmcnt(12)
	v_pk_add_f32 v[88:89], v[88:89], v[180:181]
	v_pk_add_f32 v[90:91], v[90:91], v[182:183]
	s_waitcnt vmcnt(11)
	v_pk_add_f32 v[100:101], v[100:101], v[184:185]
	v_pk_add_f32 v[102:103], v[102:103], v[186:187]
	s_waitcnt vmcnt(10)
	v_pk_add_f32 v[104:105], v[104:105], v[188:189]
	v_pk_add_f32 v[106:107], v[106:107], v[190:191]
	s_waitcnt vmcnt(9)
	v_pk_add_f32 v[108:109], v[108:109], v[192:193]
	v_pk_add_f32 v[110:111], v[110:111], v[194:195]
	s_waitcnt vmcnt(8)
	v_pk_add_f32 v[88:89], v[88:89], v[212:213]
	v_pk_add_f32 v[90:91], v[90:91], v[214:215]
	s_waitcnt vmcnt(7)
	v_pk_add_f32 v[100:101], v[100:101], v[216:217]
	v_pk_add_f32 v[102:103], v[102:103], v[218:219]
	s_waitcnt vmcnt(6)
	v_pk_add_f32 v[104:105], v[104:105], v[222:223]
	v_pk_add_f32 v[106:107], v[106:107], v[224:225]
	s_waitcnt vmcnt(5)
	v_pk_add_f32 v[108:109], v[108:109], v[226:227]
	v_pk_add_f32 v[110:111], v[110:111], v[228:229]
	s_waitcnt vmcnt(4)
	v_pk_add_f32 v[88:89], v[88:89], v[230:231]
	v_pk_add_f32 v[90:91], v[90:91], v[232:233]
	s_waitcnt vmcnt(3)
	v_pk_add_f32 v[100:101], v[100:101], v[234:235]
	v_pk_add_f32 v[102:103], v[102:103], v[236:237]
	s_waitcnt vmcnt(2)
	v_pk_add_f32 v[104:105], v[104:105], v[238:239]
	v_pk_add_f32 v[106:107], v[106:107], v[240:241]
	s_waitcnt vmcnt(1)
	v_pk_add_f32 v[108:109], v[108:109], v[242:243]
	v_pk_add_f32 v[110:111], v[110:111], v[244:245]
	s_waitcnt vmcnt(0)
	v_pk_add_f32 v[88:89], v[88:89], v[246:247]
	v_pk_add_f32 v[90:91], v[90:91], v[248:249]
	s_mov_b32 s8, 0x800000
	v_lshl_add_u64 v[206:207], v[126:127], 0, s[8:9]
	global_load_dwordx4 v[168:171], v[206:207], off
	global_load_dwordx4 v[172:175], v[206:207], off offset:1024
	global_load_dwordx4 v[176:179], v[206:207], off offset:2048
	global_load_dwordx4 v[180:183], v[206:207], off offset:3072
	s_mov_b32 s8, 0xa00000
	v_lshl_add_u64 v[198:199], v[126:127], 0, s[8:9]
	global_load_dwordx4 v[184:187], v[198:199], off
	global_load_dwordx4 v[188:191], v[198:199], off offset:1024
	global_load_dwordx4 v[192:195], v[198:199], off offset:2048
	global_load_dwordx4 v[212:215], v[198:199], off offset:3072
	s_mov_b32 s8, 0xc00000
	v_lshl_add_u64 v[206:207], v[126:127], 0, s[8:9]
	global_load_dwordx4 v[216:219], v[206:207], off
	global_load_dwordx4 v[222:225], v[206:207], off offset:1024
	global_load_dwordx4 v[226:229], v[206:207], off offset:2048
	global_load_dwordx4 v[230:233], v[206:207], off offset:3072
	s_mov_b32 s8, 0xe00000
	v_lshl_add_u64 v[198:199], v[126:127], 0, s[8:9]
	global_load_dwordx4 v[234:237], v[198:199], off
	global_load_dwordx4 v[238:241], v[198:199], off offset:1024
	global_load_dwordx4 v[242:245], v[198:199], off offset:2048
	global_load_dwordx4 v[246:249], v[198:199], off offset:3072
	s_waitcnt vmcnt(15)
	v_pk_add_f32 v[100:101], v[100:101], v[168:169]
	v_pk_add_f32 v[102:103], v[102:103], v[170:171]
	s_waitcnt vmcnt(14)
	v_pk_add_f32 v[104:105], v[104:105], v[172:173]
	v_pk_add_f32 v[106:107], v[106:107], v[174:175]
	s_waitcnt vmcnt(13)
	v_pk_add_f32 v[108:109], v[108:109], v[176:177]
	v_pk_add_f32 v[110:111], v[110:111], v[178:179]
	s_waitcnt vmcnt(12)
	v_pk_add_f32 v[88:89], v[88:89], v[180:181]
	v_pk_add_f32 v[90:91], v[90:91], v[182:183]
	s_waitcnt vmcnt(11)
	v_pk_add_f32 v[100:101], v[100:101], v[184:185]
	v_pk_add_f32 v[102:103], v[102:103], v[186:187]
	s_waitcnt vmcnt(10)
	v_pk_add_f32 v[104:105], v[104:105], v[188:189]
	v_pk_add_f32 v[106:107], v[106:107], v[190:191]
	s_waitcnt vmcnt(9)
	v_pk_add_f32 v[108:109], v[108:109], v[192:193]
	v_pk_add_f32 v[110:111], v[110:111], v[194:195]
	s_waitcnt vmcnt(8)
	v_pk_add_f32 v[88:89], v[88:89], v[212:213]
	v_pk_add_f32 v[90:91], v[90:91], v[214:215]
	s_waitcnt vmcnt(7)
	v_pk_add_f32 v[100:101], v[100:101], v[216:217]
	v_pk_add_f32 v[102:103], v[102:103], v[218:219]
	s_waitcnt vmcnt(6)
	v_pk_add_f32 v[104:105], v[104:105], v[222:223]
	v_pk_add_f32 v[106:107], v[106:107], v[224:225]
	s_waitcnt vmcnt(5)
	v_pk_add_f32 v[108:109], v[108:109], v[226:227]
	v_pk_add_f32 v[110:111], v[110:111], v[228:229]
	s_waitcnt vmcnt(4)
	v_pk_add_f32 v[88:89], v[88:89], v[230:231]
	v_pk_add_f32 v[90:91], v[90:91], v[232:233]
	s_waitcnt vmcnt(3)
	v_pk_add_f32 v[100:101], v[100:101], v[234:235]
	v_pk_add_f32 v[102:103], v[102:103], v[236:237]
	s_waitcnt vmcnt(2)
	v_pk_add_f32 v[104:105], v[104:105], v[238:239]
	v_pk_add_f32 v[106:107], v[106:107], v[240:241]
	s_waitcnt vmcnt(1)
	v_pk_add_f32 v[108:109], v[108:109], v[242:243]
	v_pk_add_f32 v[110:111], v[110:111], v[244:245]
	s_waitcnt vmcnt(0)
	v_pk_add_f32 v[88:89], v[88:89], v[246:247]
	v_pk_add_f32 v[90:91], v[90:91], v[248:249]
	s_mov_b32 s8, 0x1000000
	v_lshl_add_u64 v[206:207], v[126:127], 0, s[8:9]
	global_load_dwordx4 v[168:171], v[206:207], off
	global_load_dwordx4 v[172:175], v[206:207], off offset:1024
	global_load_dwordx4 v[176:179], v[206:207], off offset:2048
	global_load_dwordx4 v[180:183], v[206:207], off offset:3072
	s_mov_b32 s8, 0x1200000
	v_lshl_add_u64 v[198:199], v[126:127], 0, s[8:9]
	global_load_dwordx4 v[184:187], v[198:199], off
	global_load_dwordx4 v[188:191], v[198:199], off offset:1024
	global_load_dwordx4 v[192:195], v[198:199], off offset:2048
	global_load_dwordx4 v[212:215], v[198:199], off offset:3072
	s_mov_b32 s8, 0x1400000
	v_lshl_add_u64 v[206:207], v[126:127], 0, s[8:9]
	global_load_dwordx4 v[216:219], v[206:207], off
	global_load_dwordx4 v[222:225], v[206:207], off offset:1024
	global_load_dwordx4 v[226:229], v[206:207], off offset:2048
	global_load_dwordx4 v[230:233], v[206:207], off offset:3072
	s_waitcnt vmcnt(11)
	v_pk_add_f32 v[100:101], v[100:101], v[168:169]
	v_pk_add_f32 v[102:103], v[102:103], v[170:171]
	s_waitcnt vmcnt(10)
	v_pk_add_f32 v[104:105], v[104:105], v[172:173]
	v_pk_add_f32 v[106:107], v[106:107], v[174:175]
	s_waitcnt vmcnt(9)
	v_pk_add_f32 v[108:109], v[108:109], v[176:177]
	v_pk_add_f32 v[110:111], v[110:111], v[178:179]
	s_waitcnt vmcnt(8)
	v_pk_add_f32 v[88:89], v[88:89], v[180:181]
	v_pk_add_f32 v[90:91], v[90:91], v[182:183]
	s_waitcnt vmcnt(7)
	v_pk_add_f32 v[100:101], v[100:101], v[184:185]
	v_pk_add_f32 v[102:103], v[102:103], v[186:187]
	s_waitcnt vmcnt(6)
	v_pk_add_f32 v[104:105], v[104:105], v[188:189]
	v_pk_add_f32 v[106:107], v[106:107], v[190:191]
	s_waitcnt vmcnt(5)
	v_pk_add_f32 v[108:109], v[108:109], v[192:193]
	v_pk_add_f32 v[110:111], v[110:111], v[194:195]
	s_waitcnt vmcnt(4)
	v_pk_add_f32 v[88:89], v[88:89], v[212:213]
	v_pk_add_f32 v[90:91], v[90:91], v[214:215]
	s_waitcnt vmcnt(3)
	v_pk_add_f32 v[100:101], v[100:101], v[216:217]
	v_pk_add_f32 v[102:103], v[102:103], v[218:219]
	s_waitcnt vmcnt(2)
	v_pk_add_f32 v[104:105], v[104:105], v[222:223]
	v_pk_add_f32 v[106:107], v[106:107], v[224:225]
	s_waitcnt vmcnt(1)
	v_pk_add_f32 v[108:109], v[108:109], v[226:227]
	v_pk_add_f32 v[110:111], v[110:111], v[228:229]
	s_waitcnt vmcnt(0)
	v_pk_add_f32 v[88:89], v[88:89], v[230:231]
	v_pk_add_f32 v[90:91], v[90:91], v[232:233]
	s_nop 1
